# v18 plus cache-warming touches for the s5_sample per-item parameters
# speedup vs baseline: 1.0131x; 1.0012x over previous
; #define INP(i) ((const float*)(const GASP float*)kargs()[(i)])
; __device__ __forceinline__ void s5_params(int j, int g, int n, float& ar, float& ai, float (&bbr)[16], float (&bbi)[16]) {
;     const float step = expf(INP(I_LSTEP)[j * 64 + g]); const int gi = (j * 64 + g) * 64 + n;
;     const float lr = INP(I_LAMRE)[gi], li = INP(I_LAMIM)[gi], mag = expf(lr * step); float sn, cs; sincos_acc(li * step, sn, cs);
;     ar = mag * cs; ai = mag * sn;
; __device__ __forceinline__ void s5_sample(const Frame& F, int j) {
;     ...
;     for (int item = F.vcu; item < 256; item += F.G) { const int g = item >> 2, bq = item & 3, n = F.lane;
;         float ar, ai, bbr[16], bbi[16]; s5_params(j, g, n, ar, ai, bbr, bbi);
.LBB0_1583:
	s_ashr_i32 s98, s11, 2
	s_add_i32 s98, s98, s30
	v_mbcnt_lo_u32_b32 v250, -1, 0
	v_mbcnt_hi_u32_b32 v250, -1, v250
	v_lshlrev_b32_e32 v250, 6, v250
	s_lshl_b32 s99, s98, 12
	s_load_dwordx2 s[100:101], s[0:1], 0x90
	s_waitcnt lgkmcnt(0)
	s_add_u32 s100, s100, s99
	s_addc_u32 s101, s101, 0
	global_load_dword v251, v250, s[100:101]
	s_load_dwordx2 s[100:101], s[0:1], 0x98
	s_waitcnt lgkmcnt(0)
	s_add_u32 s100, s100, s99
	s_addc_u32 s101, s101, 0
	global_load_dword v251, v250, s[100:101]
	s_load_dwordx2 s[100:101], s[0:1], 0xa0
	s_waitcnt lgkmcnt(0)
	s_add_u32 s100, s100, s99
	s_addc_u32 s101, s101, 0
	global_load_dword v251, v250, s[100:101]
	s_load_dwordx2 s[100:101], s[0:1], 0xa8
	s_waitcnt lgkmcnt(0)
	s_add_u32 s100, s100, s99
	s_addc_u32 s101, s101, 0
	global_load_dword v251, v250, s[100:101]
	v_lshrrev_b32_e32 v250, 4, v250
	s_lshl_b32 s99, s98, 8
	s_load_dwordx2 s[100:101], s[0:1], 0x80
	s_waitcnt lgkmcnt(0)
	s_add_u32 s100, s100, s99
	s_addc_u32 s101, s101, 0
	global_load_dword v251, v250, s[100:101]
	s_load_dwordx2 s[100:101], s[0:1], 0x88
	s_waitcnt lgkmcnt(0)
	s_add_u32 s100, s100, s99
	s_addc_u32 s101, s101, 0
	global_load_dword v251, v250, s[100:101]
	s_mov_b64 s[12:13], s[0:1]
	s_load_dwordx2 s[16:17], s[12:13], 0xb8
	s_ashr_i32 s12, s11, 2
	s_add_i32 s36, s12, s30
	s_ashr_i32 s37, s36, 31
	s_lshl_b64 s[18:19], s[36:37], 2
	s_waitcnt lgkmcnt(0)
	s_add_u32 s16, s16, s18
	s_addc_u32 s17, s17, s19
	global_load_dword v2, v173, s[16:17]
	s_mov_b64 s[16:17], s[0:1]
	s_load_dwordx2 s[16:17], s[16:17], 0x80
	v_lshl_add_u32 v0, s36, 6, v32
	v_ashrrev_i32_e32 v1, 31, v0
	s_mov_b64 s[22:23], s[0:1]
	s_waitcnt lgkmcnt(0)
	v_lshl_add_u64 v[4:5], v[0:1], 2, s[16:17]
	global_load_dword v4, v[4:5], off
	s_load_dwordx2 s[16:17], s[22:23], 0x88
	s_waitcnt lgkmcnt(0)
	v_lshl_add_u64 v[6:7], v[0:1], 2, s[16:17]
	global_load_dword v5, v[6:7], off
	s_waitcnt vmcnt(2)
	v_mul_f32_e32 v3, 0x3fb8aa3b, v2
	v_rndne_f32_e32 v6, v3
	v_fma_f32 v7, v2, s28, -v3
	v_sub_f32_e32 v3, v3, v6
	v_fmac_f32_e32 v7, 0x32a5705f, v2
	v_add_f32_e32 v3, v3, v7
	v_cvt_i32_f32_e32 v6, v6
	v_exp_f32_e32 v3, v3
	v_cmp_ngt_f32_e32 vcc, s14, v2
	v_ldexp_f32 v3, v3, v6
	s_nop 0
	v_cndmask_b32_e32 v3, 0, v3, vcc
	v_cmp_nlt_f32_e32 vcc, s29, v2
	s_nop 1
	v_cndmask_b32_e32 v6, v221, v3, vcc
	s_waitcnt vmcnt(0)
	v_mul_f32_e32 v2, v6, v5
	v_mul_f32_e32 v3, 0x3f22f983, v2
	v_rndne_f32_e32 v3, v3
	v_fmac_f32_e32 v2, 0xbfc90000, v3
	v_cvt_i32_f32_e32 v7, v3
	v_fmac_f32_e32 v2, 0xb9fda000, v3
	v_fmac_f32_e32 v2, 0xb3a22169, v3
	v_mul_f32_e32 v11, v2, v2
	v_fmamk_f32 v3, v11, 0x3638ef1d, v218
	v_fmamk_f32 v9, v11, 0xb493f27e, v219
	v_and_b32_e32 v8, 3, v7
	v_fmaak_f32 v3, v3, v11, 0x3c088888
	v_fmaak_f32 v7, v9, v11, 0xbab60b61
	v_fmaak_f32 v3, v3, v11, 0xbe2aaaab
	v_fmaak_f32 v7, v7, v11, 0x3d2aaaab
	v_mov_b32_e32 v174, v2
	v_mul_f32_e32 v10, v11, v3
	v_fma_f32 v3, v7, v11, -0.5
	v_pk_fma_f32 v[2:3], v[10:11], v[2:3], v[174:175]
	v_cmp_lt_i32_e32 vcc, 0, v8
	v_mov_b32_e32 v7, v3
	s_and_saveexec_b64 s[22:23], vcc
	s_cbranch_execz .LBB0_1589
	v_cmp_ne_u32_e32 vcc, 1, v8
	v_xor_b32_e32 v7, 0x80000000, v2
	s_and_saveexec_b64 s[16:17], vcc
	s_xor_b64 s[74:75], exec, s[16:17]
	v_cmp_eq_u32_e32 vcc, 2, v8
	s_nop 1
	v_cndmask_b32_e32 v7, v3, v2, vcc
	v_xor_b32_e32 v8, 0x80000000, v7
	v_cndmask_b32_e64 v7, v2, -v3, vcc
	v_mov_b32_e32 v2, v8
	s_andn2_saveexec_b64 s[74:75], s[74:75]
	v_mov_b32_e32 v2, v3
	s_or_b64 exec, exec, s[74:75]
